# v45 + chunk-delta K staging unrolled, later P3 code held at the v45 code alignment
# speedup vs baseline: 1.0004x; 1.0004x over previous
; __device__ __forceinline__ float bfv(bf16 v) { return __uint_as_float((unsigned)v << 16); }
; template <int MASK> __device__ __forceinline__ void phase3(const Args& a, LAS unsigned char* lds, int tid, int wave, int lane, int vcu, int G) {
;     ...
;         for (int ub = vcu; ub < 512; ub += G)
;             { const int b = ub >> 2, hd = ub & 3;
;                 __syncthreads();
;                 for (int i = tid; i < 3072; i += NTHREADS) { const int which = i >> 10, t = (i >> 7) & 7, d = i & 127; const size_t R = NP + 8 * b + t;
;                     QS[i] = which == 0 ? bfv(P1[R * P1W + C_MQ + hd * 128 + d]) : which == 1 ? bfv(P1[R * P1W + C_MK + hd * 128 + d]) : bfv(PT[(size_t)(R_MVT + hd * 128 + d) * MT + R]); }
.LBB0_699:
	s_or_b64 exec, exec, s[54:55]
	v_readlane_b32 s2, v253, 2
	s_add_i32 s46, s46, s2
	s_cmpk_gt_i32 s46, 0x1ff
	v_readlane_b32 s3, v253, 3
	s_cbranch_scc1 .LBB0_740
	s_branch .Lpinc_0
	.p2align 8
	s_nop 0
	s_nop 0
	s_nop 0
	s_nop 0
	s_nop 0
	s_nop 0
	s_nop 0
	s_nop 0
	s_nop 0
	s_nop 0
	s_nop 0
	s_nop 0
	s_nop 0
	s_nop 0
	s_nop 0
	s_nop 0
	s_nop 0
	s_nop 0
	s_nop 0
	s_nop 0
	s_nop 0
	s_nop 0
	s_nop 0
	s_nop 0
	s_nop 0
	s_nop 0
	s_nop 0
	s_nop 0
	s_nop 0
	s_nop 0
	s_nop 0
	s_nop 0
	s_nop 0
	s_nop 0
	s_nop 0
	s_nop 0
	s_nop 0
	s_nop 0
	s_nop 0
	s_nop 0
	s_nop 0
	s_nop 0
	s_nop 0
	s_nop 0
	s_nop 0
	s_nop 0
	s_nop 0
.Lpinc_0:
.LBB0_700:
	s_and_b32 s37, s46, 3
	s_mov_b32 s4, s94
	s_lshl_b32 s94, s37, 7
	v_or_b32_e32 v2, s94, v108
	s_lshl_b32 s2, s46, 1
	v_mul_u32_u24_e32 v2, 0x4400, v2
	s_and_b32 s48, s2, -8
	v_lshlrev_b32_e32 v94, 1, v2
	s_lshl_b32 s52, s37, 8
	s_add_i32 s54, s48, 0x4000
	s_waitcnt lgkmcnt(0)
	v_lshl_add_u64 v[2:3], s[58:59], 0, v[94:95]
	v_lshl_add_u64 v[4:5], v[138:139], 0, s[52:53]
	v_add_u32_e32 v170, s54, v223
	v_add_u32_e32 v171, 4, v170
	s_mov_b64 s[88:89], 0x800
	v_mad_i64_i32 v[172:173], s[2:3], v170, s95, v[4:5]
	v_mad_i64_i32 v[174:175], s[2:3], v171, s95, v[4:5]
	global_load_ushort v182, v[172:173], off offset:2048
	global_load_ushort v183, v[174:175], off offset:2048
	v_lshl_add_u64 v[172:173], v[172:173], 0, s[88:89]
	v_lshl_add_u64 v[174:175], v[174:175], 0, s[88:89]
	global_load_ushort v184, v[172:173], off offset:2048
	global_load_ushort v185, v[174:175], off offset:2048
	v_mad_u64_u32 v[176:177], s[2:3], v170, 2, v[2:3]
	v_mad_u64_u32 v[178:179], s[2:3], v171, 2, v[2:3]
	global_load_ushort v186, v[176:177], off
	global_load_ushort v187, v[178:179], off
	s_barrier
	s_waitcnt vmcnt(5)
	v_lshlrev_b32_e32 v182, 16, v182
	ds_write_b32 v216, v182
	s_waitcnt vmcnt(4)
	v_lshlrev_b32_e32 v183, 16, v183
	ds_write_b32 v216, v183 offset:2048
	s_waitcnt vmcnt(3)
	v_lshlrev_b32_e32 v184, 16, v184
	ds_write_b32 v216, v184 offset:4096
	s_waitcnt vmcnt(2)
	v_lshlrev_b32_e32 v185, 16, v185
	ds_write_b32 v216, v185 offset:6144
	s_waitcnt vmcnt(1)
	v_lshlrev_b32_e32 v186, 16, v186
	ds_write_b32 v216, v186 offset:8192
	s_waitcnt vmcnt(0)
	v_lshlrev_b32_e32 v187, 16, v187
	ds_write_b32 v216, v187 offset:10240
	s_and_saveexec_b64 s[88:89], s[30:31]
	s_cbranch_execz .LBB0_712
; template <int MASK> __device__ __forceinline__ void phase3(const Args& a, LAS unsigned char* lds, int tid, int wave, int lane, int vcu, int G) {
;     ...
;                 if (tid == 0) {
;                     const float m0 = a.in[6][b * 4 + hd]; float F = 0.f, cm = m0; float bb[8];
; #pragma unroll
;                     for (int t = 0; t < 8; ++t) { const size_t R = NP + 8 * b + t; F += LF[R * 4 + hd]; bb[t] = IG[R * 4 + hd] - F; cm = fmaxf(cm, bb[t]);
;                         SC[t] = F; SC[8 + t] = bb[t]; SC[16 + t] = cm; SC[24 + t] = __expf(m0 - cm); SC[32 + t] = F + cm; }
; #pragma unroll
;                     for (int s = 0; s < 8; ++s) SC[40 + s] = __expf(bb[s] - cm);
;                     SC[48] = __expf(m0 - cm); SC[49] = F + cm;
;                 }
	s_ashr_i32 s47, s46, 31
	v_readlane_b32 s8, v253, 11
	s_lshl_b64 s[2:3], s[46:47], 2
	v_readlane_b32 s20, v253, 23
	v_readlane_b32 s21, v253, 24
	s_add_u32 s2, s20, s2
	s_addc_u32 s3, s21, s3
	s_ashr_i32 s55, s54, 31
	global_load_dword v30, v95, s[2:3]
	s_lshl_b64 s[2:3], s[54:55], 4
	s_lshl_b32 s47, s37, 2
	s_or_b32 s2, s2, s47
	s_add_u32 s68, s78, s2
	s_addc_u32 s69, s79, s3
	s_add_u32 s2, s74, s2
	s_addc_u32 s3, s75, s3
	s_ashr_i32 s49, s48, 31
	s_lshl_b64 s[90:91], s[48:49], 4
	s_or_b32 s47, s90, s47
	s_add_u32 s49, s47, 0x40010
	s_addc_u32 s52, s91, 0
	global_load_dword v8, v95, s[68:69]
	global_load_dword v3, v95, s[2:3]
	s_add_u32 s2, s78, s49
	s_addc_u32 s3, s79, s52
	global_load_dword v9, v95, s[2:3]
	s_add_u32 s2, s74, s49
	s_addc_u32 s3, s75, s52
	s_add_u32 s49, s47, 0x40020
	s_addc_u32 s52, s91, 0
	global_load_dword v4, v95, s[2:3]
	s_add_u32 s2, s78, s49
	s_addc_u32 s3, s79, s52
	global_load_dword v10, v95, s[2:3]
	s_add_u32 s2, s74, s49
	s_addc_u32 s3, s75, s52
	s_add_u32 s49, s47, 0x40030
	s_addc_u32 s52, s91, 0
	global_load_dword v5, v95, s[2:3]
	s_add_u32 s2, s78, s49
	s_addc_u32 s3, s79, s52
	global_load_dword v11, v95, s[2:3]
	s_add_u32 s2, s74, s49
	s_addc_u32 s3, s75, s52
	s_add_u32 s49, s47, 0x40040
	s_addc_u32 s52, s91, 0
	global_load_dword v6, v95, s[2:3]
	s_add_u32 s2, s78, s49
	s_addc_u32 s3, s79, s52
	global_load_dword v18, v95, s[2:3]
	s_add_u32 s2, s74, s49
	s_addc_u32 s3, s75, s52
	s_add_u32 s49, s47, 0x40050
	s_addc_u32 s52, s91, 0
	global_load_dword v7, v95, s[2:3]
	s_add_u32 s2, s78, s49
	s_addc_u32 s3, s79, s52
	global_load_dword v19, v95, s[2:3]
	s_add_u32 s2, s74, s49
	s_addc_u32 s3, s75, s52
	s_add_u32 s49, s47, 0x40060
	s_addc_u32 s52, s91, 0
	global_load_dword v12, v95, s[2:3]
	s_add_u32 s2, s78, s49
	s_addc_u32 s3, s79, s52
	global_load_dword v20, v95, s[2:3]
	s_add_u32 s2, s74, s49
	s_addc_u32 s3, s75, s52
	s_add_u32 s47, s47, 0x40070
	s_addc_u32 s49, s91, 0
	global_load_dword v13, v95, s[2:3]
	s_add_u32 s2, s78, s47
	s_addc_u32 s3, s79, s49
	global_load_dword v2, v95, s[2:3]
	s_add_u32 s2, s74, s47
	s_addc_u32 s3, s75, s49
	global_load_dword v31, v95, s[2:3]
	v_readlane_b32 s2, v254, 37
	v_readlane_b32 s10, v253, 13
	v_readlane_b32 s11, v253, 14
	v_mov_b32_e32 v22, s2
	v_readlane_b32 s2, v254, 39
	v_readlane_b32 s12, v253, 15
	v_readlane_b32 s13, v253, 16
	v_mov_b32_e32 v24, s2
	v_readlane_b32 s2, v254, 41
	v_readlane_b32 s14, v253, 17
	v_readlane_b32 s15, v253, 18
	v_mov_b32_e32 v26, s2
	s_waitcnt vmcnt(16)
	v_max_f32_e32 v33, v30, v30
	v_readlane_b32 s2, v254, 43
	v_readlane_b32 s16, v253, 19
	v_readlane_b32 s17, v253, 20
	v_mov_b32_e32 v32, s2
	v_readlane_b32 s18, v253, 21
	s_movk_i32 s18, 0x3000
	s_movk_i32 s17, 0x2000
	s_movk_i32 s16, 0x4000
	s_mov_b32 s15, s38
	s_mov_b32 s14, s28
	s_mov_b32 s13, s36
	s_waitcnt vmcnt(15)
	v_add_f32_e32 v8, 0, v8
	v_mov_b32_e32 v21, v8
	s_mov_b32 s12, s73
	s_mov_b32 s11, s72
	s_waitcnt vmcnt(13)
	v_add_f32_e32 v9, v8, v9
	v_mov_b32_e32 v14, v9
	s_mov_b32 s10, s67
	v_readlane_b32 s9, v253, 12
	v_readlane_b32 s19, v253, 22
	v_readlane_b32 s22, v253, 25
	v_readlane_b32 s23, v253, 26
	s_waitcnt vmcnt(11)
	v_add_f32_e32 v15, v9, v10
	v_mov_b32_e32 v10, v15
	s_waitcnt vmcnt(10)
	v_pk_add_f32 v[16:17], v[4:5], v[14:15] neg_lo:[0,1] neg_hi:[0,1]
	ds_write2_b32 v22, v16, v17 offset1:1
	s_waitcnt vmcnt(9)
	v_add_f32_e32 v11, v15, v11
	v_mov_b32_e32 v14, v11
	ds_write_b128 v95, v[8:11] offset:12288
	s_waitcnt vmcnt(7)
	v_add_f32_e32 v15, v11, v18
	v_mov_b32_e32 v18, v15
	v_mov_b32_e32 v4, v15
	s_waitcnt vmcnt(6)
	v_pk_add_f32 v[22:23], v[6:7], v[14:15] neg_lo:[0,1] neg_hi:[0,1]
	ds_write2_b32 v24, v22, v23 offset1:1
	s_waitcnt vmcnt(5)
	v_add_f32_e32 v14, v15, v19
	v_mov_b32_e32 v5, v14
	v_mov_b32_e32 v19, v14
	s_waitcnt vmcnt(3)
	v_add_f32_e32 v20, v14, v20
	v_mov_b32_e32 v15, v20
	v_mov_b32_e32 v6, v20
	s_waitcnt vmcnt(2)
	v_pk_add_f32 v[24:25], v[12:13], v[14:15] neg_lo:[0,1] neg_hi:[0,1]
	ds_write_b96 v95, v[4:6] offset:12304
	ds_write2_b32 v26, v24, v25 offset1:1
	s_waitcnt vmcnt(1)
	v_pk_add_f32 v[28:29], v[2:3], v[20:21] neg_lo:[0,1] neg_hi:[0,1]
	v_pk_add_f32 v[26:27], v[2:3], v[20:21]
	v_max_f32_e32 v2, v33, v29
	v_sub_f32_e32 v4, v30, v2
	v_max_f32_e32 v3, v2, v16
	v_mul_f32_e32 v5, 0x3fb8aa3b, v4
	v_max_f32_e32 v4, v3, v17
	v_sub_f32_e32 v13, v30, v3
	v_exp_f32_e32 v12, v5
	v_max_f32_e32 v5, v4, v22
	v_pk_add_f32 v[6:7], v[8:9], v[2:3]
	v_mul_f32_e32 v8, 0x3fb8aa3b, v13
	v_sub_f32_e32 v9, v30, v4
	ds_write_b128 v95, v[2:5] offset:12352
	v_sub_f32_e32 v3, v30, v5
	v_max_f32_e32 v2, v5, v23
	v_exp_f32_e32 v13, v8
	v_mul_f32_e32 v14, 0x3fb8aa3b, v9
	v_pk_add_f32 v[8:9], v[10:11], v[4:5]
	v_mul_f32_e32 v4, 0x3fb8aa3b, v3
	v_sub_f32_e32 v5, v30, v2
	v_max_f32_e32 v3, v2, v24
	s_waitcnt vmcnt(0)
	v_sub_f32_e32 v27, v31, v26
	v_exp_f32_e32 v15, v4
	v_mul_f32_e32 v5, 0x3fb8aa3b, v5
	v_max_f32_e32 v4, v3, v25
	v_exp_f32_e32 v14, v14
	ds_write_b128 v95, v[6:9] offset:12416
	v_exp_f32_e32 v8, v5
	v_max_f32_e32 v5, v4, v27
	v_sub_f32_e32 v9, v30, v3
	v_sub_f32_e32 v10, v30, v4
	v_sub_f32_e32 v11, v30, v5
	v_mul_f32_e32 v9, 0x3fb8aa3b, v9
	v_mul_f32_e32 v10, 0x3fb8aa3b, v10
	v_mul_f32_e32 v11, 0x3fb8aa3b, v11
	v_exp_f32_e32 v9, v9
	v_exp_f32_e32 v10, v10
	v_exp_f32_e32 v11, v11
	v_pk_add_f32 v[6:7], v[18:19], v[2:3]
	ds_write_b128 v95, v[12:15] offset:12384
	ds_write2_b32 v32, v26, v29 offset1:1
	ds_write_b32 v95, v27 offset:12348
	ds_write_b128 v95, v[2:5] offset:12368
	ds_write_b128 v95, v[8:11] offset:12400
	v_sub_f32_e32 v2, v29, v5
	v_mul_f32_e32 v2, 0x3fb8aa3b, v2
	v_exp_f32_e32 v12, v2
	v_sub_f32_e32 v2, v16, v5
	v_mul_f32_e32 v2, 0x3fb8aa3b, v2
	v_exp_f32_e32 v13, v2
	v_sub_f32_e32 v2, v17, v5
	v_mul_f32_e32 v2, 0x3fb8aa3b, v2
	v_exp_f32_e32 v14, v2
	v_sub_f32_e32 v2, v22, v5
	v_mul_f32_e32 v2, 0x3fb8aa3b, v2
	v_exp_f32_e32 v15, v2
	v_sub_f32_e32 v2, v23, v5
	v_mul_f32_e32 v2, 0x3fb8aa3b, v2
	v_exp_f32_e32 v16, v2
	v_sub_f32_e32 v2, v24, v5
	v_mul_f32_e32 v2, 0x3fb8aa3b, v2
	v_exp_f32_e32 v17, v2
	v_sub_f32_e32 v2, v25, v5
	v_mul_f32_e32 v2, 0x3fb8aa3b, v2
	v_exp_f32_e32 v18, v2
	v_sub_f32_e32 v2, v27, v5
	v_mul_f32_e32 v2, 0x3fb8aa3b, v2
	v_mov_b32_e32 v21, v26
	v_exp_f32_e32 v19, v2
	v_pk_add_f32 v[8:9], v[20:21], v[4:5]
	ds_write_b128 v95, v[6:9] offset:12432
	ds_write_b128 v95, v[12:15] offset:12448
	ds_write_b128 v95, v[16:19] offset:12464
	v_mov_b32_e32 v8, v11
	ds_write_b64 v95, v[8:9] offset:12480
